# GEMM K-loops: priority raise moved ahead of the barrier and redundant lgkmcnt wait dropped so the MFMA burst starts right after the barrier; priority drop moved behind the closing barrier
# speedup vs baseline: 1.0045x; 1.0045x over previous
.LBB0_673:
	s_add_u32 s20, s18, 0xfff80080
	s_addc_u32 s21, s19, -1
	s_add_i32 s51, 0, 0x10000
	s_cmp_eq_u32 s49, 28
	s_cselect_b32 s23, s11, s21
	s_cselect_b32 s22, s46, s20
	v_add_u32_e32 v143, s51, v140
	s_cselect_b32 s21, s9, s48
	s_cselect_b32 s20, s47, s50
	s_add_i32 s56, 0, 0x14000
	ds_read_b128 v[144:147], v143
	ds_read_b128 v[148:151], v143 offset:1024
	ds_read_b128 v[152:155], v143 offset:2048
	ds_read_b128 v[156:159], v143 offset:3072
	v_add_u32_e32 v143, s56, v140
	ds_read_b128 v[160:163], v143
	ds_read_b128 v[164:167], v143 offset:1024
	ds_read_b128 v[168:171], v143 offset:2048
	ds_read_b128 v[172:175], v143 offset:3072
	v_lshl_add_u64 v[210:211], s[18:19], 0, v[134:135]
	s_add_i32 m0, s13, 0xc000
	ds_read_b128 v[178:181], v142
	ds_read_b128 v[182:185], v142 offset:1024
	ds_read_b128 v[186:189], v142 offset:2048
	ds_read_b128 v[190:193], v142 offset:3072
	ds_read_b128 v[194:197], v142 offset:4096
	ds_read_b128 v[198:201], v142 offset:5120
	ds_read_b128 v[202:205], v142 offset:6144
	ds_read_b128 v[206:209], v142 offset:7168
	global_load_lds_dwordx4 v[210:211], off
	v_lshl_add_u64 v[210:211], s[18:19], 0, v[136:137]
	s_add_i32 m0, s13, 0xe000
	s_nop 0
	global_load_lds_dwordx4 v[210:211], off
	s_waitcnt vmcnt(8)
	s_waitcnt lgkmcnt(0)
	s_setprio 1
	s_barrier
	v_mfma_f32_16x16x32_bf16 v[124:127], v[144:147], v[178:181], v[124:127]
	v_mfma_f32_16x16x32_bf16 v[120:123], v[152:155], v[178:181], v[120:123]
	v_mfma_f32_16x16x32_bf16 v[116:119], v[144:147], v[186:189], v[116:119]
	v_mfma_f32_16x16x32_bf16 v[112:115], v[152:155], v[186:189], v[112:115]
	v_mfma_f32_16x16x32_bf16 v[100:103], v[144:147], v[194:197], v[100:103]
	v_mfma_f32_16x16x32_bf16 v[96:99], v[152:155], v[194:197], v[96:99]
	v_mfma_f32_16x16x32_bf16 v[84:87], v[144:147], v[202:205], v[84:87]
	v_mfma_f32_16x16x32_bf16 v[80:83], v[152:155], v[202:205], v[80:83]
	v_mfma_f32_16x16x32_bf16 v[124:127], v[148:151], v[182:185], v[124:127]
	v_mfma_f32_16x16x32_bf16 v[120:123], v[156:159], v[182:185], v[120:123]
	v_mfma_f32_16x16x32_bf16 v[116:119], v[148:151], v[190:193], v[116:119]
	v_mfma_f32_16x16x32_bf16 v[112:115], v[156:159], v[190:193], v[112:115]
	v_mfma_f32_16x16x32_bf16 v[100:103], v[148:151], v[198:201], v[100:103]
	v_mfma_f32_16x16x32_bf16 v[96:99], v[156:159], v[198:201], v[96:99]
	v_mfma_f32_16x16x32_bf16 v[84:87], v[148:151], v[206:209], v[84:87]
	v_mfma_f32_16x16x32_bf16 v[80:83], v[156:159], v[206:209], v[80:83]
	s_setprio 0
	s_setprio 1
	v_mfma_f32_16x16x32_bf16 v[108:111], v[160:163], v[178:181], v[108:111]
	v_mfma_f32_16x16x32_bf16 v[104:107], v[168:171], v[178:181], v[104:107]
	v_mfma_f32_16x16x32_bf16 v[92:95], v[160:163], v[186:189], v[92:95]
	v_mfma_f32_16x16x32_bf16 v[88:91], v[168:171], v[186:189], v[88:91]
	v_mfma_f32_16x16x32_bf16 v[76:79], v[160:163], v[194:197], v[76:79]
	v_mfma_f32_16x16x32_bf16 v[72:75], v[168:171], v[194:197], v[72:75]
	v_mfma_f32_16x16x32_bf16 v[68:71], v[160:163], v[202:205], v[68:71]
	v_mfma_f32_16x16x32_bf16 v[64:67], v[168:171], v[202:205], v[64:67]
	v_mfma_f32_16x16x32_bf16 v[108:111], v[164:167], v[182:185], v[108:111]
	v_mfma_f32_16x16x32_bf16 v[104:107], v[172:175], v[182:185], v[104:107]
	v_mfma_f32_16x16x32_bf16 v[92:95], v[164:167], v[190:193], v[92:95]
	v_mfma_f32_16x16x32_bf16 v[88:91], v[172:175], v[190:193], v[88:91]
	v_mfma_f32_16x16x32_bf16 v[76:79], v[164:167], v[198:201], v[76:79]
	v_mfma_f32_16x16x32_bf16 v[72:75], v[172:175], v[198:201], v[72:75]
	v_mfma_f32_16x16x32_bf16 v[68:71], v[164:167], v[206:209], v[68:71]
	v_mfma_f32_16x16x32_bf16 v[64:67], v[172:175], v[206:209], v[64:67]
	s_barrier
	s_setprio 0
	s_add_i32 s51, s51, s28
	v_lshl_add_u64 v[210:211], s[20:21], 0, v[176:177]
	s_mov_b32 m0, s51
	ds_read_b128 v[178:181], v142 offset:16384
	ds_read_b128 v[182:185], v142 offset:17408
	ds_read_b128 v[186:189], v142 offset:18432
	ds_read_b128 v[190:193], v142 offset:19456
	ds_read_b128 v[194:197], v142 offset:20480
	ds_read_b128 v[198:201], v142 offset:21504
	ds_read_b128 v[202:205], v142 offset:22528
	ds_read_b128 v[206:209], v142 offset:23552
	global_load_lds_dwordx4 v[210:211], off
	s_add_i32 m0, s51, 0x2000
	s_add_u32 s54, s20, 0x80000
	v_lshl_add_u64 v[212:213], s[20:21], 0, v[128:129]
	s_addc_u32 s55, s21, 0
	s_add_i32 s51, s56, s28
	global_load_lds_dwordx4 v[212:213], off
	v_lshl_add_u64 v[220:221], s[54:55], 0, v[176:177]
	s_mov_b32 m0, s51
	v_lshl_add_u64 v[222:223], s[22:23], 0, v[130:131]
	global_load_lds_dwordx4 v[220:221], off
	v_lshl_add_u64 v[220:221], s[54:55], 0, v[128:129]
	s_add_i32 m0, s51, 0x2000
	s_nop 0
	global_load_lds_dwordx4 v[220:221], off
	v_lshl_add_u64 v[220:221], s[22:23], 0, v[132:133]
	s_mov_b32 m0, s13
	s_nop 0
	global_load_lds_dwordx4 v[220:221], off
	s_mov_b32 m0, s30
	s_nop 0
	global_load_lds_dwordx4 v[222:223], off
	s_waitcnt vmcnt(8)
	s_waitcnt lgkmcnt(0)
	s_setprio 1
	s_barrier
	v_mfma_f32_16x16x32_bf16 v[60:63], v[144:147], v[178:181], v[60:63]
	v_mfma_f32_16x16x32_bf16 v[56:59], v[152:155], v[178:181], v[56:59]
	v_mfma_f32_16x16x32_bf16 v[52:55], v[144:147], v[186:189], v[52:55]
	v_mfma_f32_16x16x32_bf16 v[48:51], v[152:155], v[186:189], v[48:51]
	v_mfma_f32_16x16x32_bf16 v[36:39], v[144:147], v[194:197], v[36:39]
	v_mfma_f32_16x16x32_bf16 v[32:35], v[152:155], v[194:197], v[32:35]
	v_mfma_f32_16x16x32_bf16 v[20:23], v[144:147], v[202:205], v[20:23]
	v_mfma_f32_16x16x32_bf16 v[16:19], v[152:155], v[202:205], v[16:19]
	v_mfma_f32_16x16x32_bf16 v[60:63], v[148:151], v[182:185], v[60:63]
	v_mfma_f32_16x16x32_bf16 v[56:59], v[156:159], v[182:185], v[56:59]
	v_mfma_f32_16x16x32_bf16 v[52:55], v[148:151], v[190:193], v[52:55]
	v_mfma_f32_16x16x32_bf16 v[48:51], v[156:159], v[190:193], v[48:51]
	v_mfma_f32_16x16x32_bf16 v[36:39], v[148:151], v[198:201], v[36:39]
	v_mfma_f32_16x16x32_bf16 v[32:35], v[156:159], v[198:201], v[32:35]
	v_mfma_f32_16x16x32_bf16 v[20:23], v[148:151], v[206:209], v[20:23]
	v_mfma_f32_16x16x32_bf16 v[16:19], v[156:159], v[206:209], v[16:19]
	s_setprio 0
	s_setprio 1
	v_mfma_f32_16x16x32_bf16 v[44:47], v[160:163], v[178:181], v[44:47]
	v_mfma_f32_16x16x32_bf16 v[40:43], v[168:171], v[178:181], v[40:43]
	v_mfma_f32_16x16x32_bf16 v[28:31], v[160:163], v[186:189], v[28:31]
	v_mfma_f32_16x16x32_bf16 v[24:27], v[168:171], v[186:189], v[24:27]
	v_mfma_f32_16x16x32_bf16 v[12:15], v[160:163], v[194:197], v[12:15]
	v_mfma_f32_16x16x32_bf16 v[8:11], v[168:171], v[194:197], v[8:11]
	v_mfma_f32_16x16x32_bf16 v[4:7], v[160:163], v[202:205], v[4:7]
	v_mfma_f32_16x16x32_bf16 v[0:3], v[168:171], v[202:205], v[0:3]
	v_mfma_f32_16x16x32_bf16 v[44:47], v[164:167], v[182:185], v[44:47]
	v_mfma_f32_16x16x32_bf16 v[40:43], v[172:175], v[182:185], v[40:43]
	v_mfma_f32_16x16x32_bf16 v[28:31], v[164:167], v[190:193], v[28:31]
	v_mfma_f32_16x16x32_bf16 v[24:27], v[172:175], v[190:193], v[24:27]
	v_mfma_f32_16x16x32_bf16 v[12:15], v[164:167], v[198:201], v[12:15]
	v_mfma_f32_16x16x32_bf16 v[8:11], v[172:175], v[198:201], v[8:11]
	v_mfma_f32_16x16x32_bf16 v[4:7], v[164:167], v[206:209], v[4:7]
	v_mfma_f32_16x16x32_bf16 v[0:3], v[172:175], v[206:209], v[0:3]
	s_barrier
	s_setprio 0
	s_add_i32 s51, 0, 0x18000
	v_add_u32_e32 v143, s51, v140
	s_add_i32 s54, 0, 0x1c000
	ds_read_b128 v[144:147], v143
	ds_read_b128 v[148:151], v143 offset:1024
	ds_read_b128 v[152:155], v143 offset:2048
	ds_read_b128 v[156:159], v143 offset:3072
	v_add_u32_e32 v143, s54, v140
	ds_read_b128 v[160:163], v143
	ds_read_b128 v[164:167], v143 offset:1024
	ds_read_b128 v[168:171], v143 offset:2048
	ds_read_b128 v[172:175], v143 offset:3072
	s_add_u32 s22, s22, 0x80000
	s_addc_u32 s23, s23, 0
	s_mov_b32 m0, s31
	v_lshl_add_u64 v[232:233], s[22:23], 0, v[132:133]
	ds_read_b128 v[178:181], v142 offset:32768
	ds_read_b128 v[182:185], v142 offset:33792
	ds_read_b128 v[186:189], v142 offset:34816
	ds_read_b128 v[190:193], v142 offset:35840
	ds_read_b128 v[194:197], v142 offset:36864
	ds_read_b128 v[198:201], v142 offset:37888
	ds_read_b128 v[202:205], v142 offset:38912
	ds_read_b128 v[206:209], v142 offset:39936
	global_load_lds_dwordx4 v[232:233], off
	v_lshl_add_u64 v[232:233], s[22:23], 0, v[130:131]
	s_mov_b32 m0, s33
	s_nop 0
	global_load_lds_dwordx4 v[232:233], off
	s_waitcnt vmcnt(8)
	s_waitcnt lgkmcnt(0)
	s_setprio 1
	s_barrier
	v_mfma_f32_16x16x32_bf16 v[124:127], v[144:147], v[178:181], v[124:127]
	v_mfma_f32_16x16x32_bf16 v[120:123], v[152:155], v[178:181], v[120:123]
	v_mfma_f32_16x16x32_bf16 v[116:119], v[144:147], v[186:189], v[116:119]
	v_mfma_f32_16x16x32_bf16 v[112:115], v[152:155], v[186:189], v[112:115]
	v_mfma_f32_16x16x32_bf16 v[100:103], v[144:147], v[194:197], v[100:103]
	v_mfma_f32_16x16x32_bf16 v[96:99], v[152:155], v[194:197], v[96:99]
	v_mfma_f32_16x16x32_bf16 v[84:87], v[144:147], v[202:205], v[84:87]
	v_mfma_f32_16x16x32_bf16 v[80:83], v[152:155], v[202:205], v[80:83]
	v_mfma_f32_16x16x32_bf16 v[124:127], v[148:151], v[182:185], v[124:127]
	v_mfma_f32_16x16x32_bf16 v[120:123], v[156:159], v[182:185], v[120:123]
	v_mfma_f32_16x16x32_bf16 v[116:119], v[148:151], v[190:193], v[116:119]
	v_mfma_f32_16x16x32_bf16 v[112:115], v[156:159], v[190:193], v[112:115]
	v_mfma_f32_16x16x32_bf16 v[100:103], v[148:151], v[198:201], v[100:103]
	v_mfma_f32_16x16x32_bf16 v[96:99], v[156:159], v[198:201], v[96:99]
	v_mfma_f32_16x16x32_bf16 v[84:87], v[148:151], v[206:209], v[84:87]
	v_mfma_f32_16x16x32_bf16 v[80:83], v[156:159], v[206:209], v[80:83]
	s_setprio 0
	s_setprio 1
	v_mfma_f32_16x16x32_bf16 v[108:111], v[160:163], v[178:181], v[108:111]
	v_mfma_f32_16x16x32_bf16 v[104:107], v[168:171], v[178:181], v[104:107]
	v_mfma_f32_16x16x32_bf16 v[92:95], v[160:163], v[186:189], v[92:95]
	v_mfma_f32_16x16x32_bf16 v[88:91], v[168:171], v[186:189], v[88:91]
	v_mfma_f32_16x16x32_bf16 v[76:79], v[160:163], v[194:197], v[76:79]
	v_mfma_f32_16x16x32_bf16 v[72:75], v[168:171], v[194:197], v[72:75]
	v_mfma_f32_16x16x32_bf16 v[68:71], v[160:163], v[202:205], v[68:71]
	v_mfma_f32_16x16x32_bf16 v[64:67], v[168:171], v[202:205], v[64:67]
	v_mfma_f32_16x16x32_bf16 v[108:111], v[164:167], v[182:185], v[108:111]
	v_mfma_f32_16x16x32_bf16 v[104:107], v[172:175], v[182:185], v[104:107]
	v_mfma_f32_16x16x32_bf16 v[92:95], v[164:167], v[190:193], v[92:95]
	v_mfma_f32_16x16x32_bf16 v[88:91], v[172:175], v[190:193], v[88:91]
	v_mfma_f32_16x16x32_bf16 v[76:79], v[164:167], v[198:201], v[76:79]
	v_mfma_f32_16x16x32_bf16 v[72:75], v[172:175], v[198:201], v[72:75]
	v_mfma_f32_16x16x32_bf16 v[68:71], v[164:167], v[206:209], v[68:71]
	v_mfma_f32_16x16x32_bf16 v[64:67], v[172:175], v[206:209], v[64:67]
	s_barrier
	s_setprio 0
	s_add_i32 s22, s51, s28
	v_lshl_add_u64 v[210:211], v[210:211], 0, s[40:41]
	s_mov_b32 m0, s22
	ds_read_b128 v[178:181], v142 offset:49152
	ds_read_b128 v[182:185], v142 offset:50176
	ds_read_b128 v[186:189], v142 offset:51200
	ds_read_b128 v[190:193], v142 offset:52224
	ds_read_b128 v[194:197], v142 offset:53248
	ds_read_b128 v[198:201], v142 offset:54272
	ds_read_b128 v[202:205], v142 offset:55296
	ds_read_b128 v[206:209], v142 offset:56320
	global_load_lds_dwordx4 v[210:211], off
	s_add_i32 m0, s22, 0x2000
	s_add_u32 s20, s20, 0x80080
	v_lshl_add_u64 v[210:211], v[212:213], 0, s[40:41]
	s_addc_u32 s21, s21, 0
	s_add_i32 s22, s54, s28
	global_load_lds_dwordx4 v[210:211], off
	v_lshl_add_u64 v[210:211], s[20:21], 0, v[176:177]
	s_mov_b32 m0, s22
	s_nop 0
	global_load_lds_dwordx4 v[210:211], off
	v_lshl_add_u64 v[210:211], s[20:21], 0, v[128:129]
	s_add_i32 m0, s22, 0x2000
	s_nop 0
	global_load_lds_dwordx4 v[210:211], off
	v_lshl_add_u64 v[210:211], v[220:221], 0, s[40:41]
	s_mov_b32 m0, s34
	s_nop 0
	global_load_lds_dwordx4 v[210:211], off
	v_lshl_add_u64 v[210:211], v[222:223], 0, s[40:41]
	s_mov_b32 m0, s35
	s_nop 0
	global_load_lds_dwordx4 v[210:211], off
	s_waitcnt vmcnt(8)
	s_waitcnt lgkmcnt(0)
	s_setprio 1
	s_barrier
	v_mfma_f32_16x16x32_bf16 v[60:63], v[144:147], v[178:181], v[60:63]
	v_mfma_f32_16x16x32_bf16 v[56:59], v[152:155], v[178:181], v[56:59]
	v_mfma_f32_16x16x32_bf16 v[52:55], v[144:147], v[186:189], v[52:55]
	v_mfma_f32_16x16x32_bf16 v[48:51], v[152:155], v[186:189], v[48:51]
	v_mfma_f32_16x16x32_bf16 v[36:39], v[144:147], v[194:197], v[36:39]
	v_mfma_f32_16x16x32_bf16 v[32:35], v[152:155], v[194:197], v[32:35]
	v_mfma_f32_16x16x32_bf16 v[20:23], v[144:147], v[202:205], v[20:23]
	v_mfma_f32_16x16x32_bf16 v[16:19], v[152:155], v[202:205], v[16:19]
	v_mfma_f32_16x16x32_bf16 v[60:63], v[148:151], v[182:185], v[60:63]
	v_mfma_f32_16x16x32_bf16 v[56:59], v[156:159], v[182:185], v[56:59]
	v_mfma_f32_16x16x32_bf16 v[52:55], v[148:151], v[190:193], v[52:55]
	v_mfma_f32_16x16x32_bf16 v[48:51], v[156:159], v[190:193], v[48:51]
	v_mfma_f32_16x16x32_bf16 v[36:39], v[148:151], v[198:201], v[36:39]
	v_mfma_f32_16x16x32_bf16 v[32:35], v[156:159], v[198:201], v[32:35]
	v_mfma_f32_16x16x32_bf16 v[20:23], v[148:151], v[206:209], v[20:23]
	v_mfma_f32_16x16x32_bf16 v[16:19], v[156:159], v[206:209], v[16:19]
	s_setprio 0
	s_setprio 1
	v_mfma_f32_16x16x32_bf16 v[44:47], v[160:163], v[178:181], v[44:47]
	v_mfma_f32_16x16x32_bf16 v[40:43], v[168:171], v[178:181], v[40:43]
	v_mfma_f32_16x16x32_bf16 v[28:31], v[160:163], v[186:189], v[28:31]
	v_mfma_f32_16x16x32_bf16 v[24:27], v[168:171], v[186:189], v[24:27]
	v_mfma_f32_16x16x32_bf16 v[12:15], v[160:163], v[194:197], v[12:15]
	v_mfma_f32_16x16x32_bf16 v[8:11], v[168:171], v[194:197], v[8:11]
	v_mfma_f32_16x16x32_bf16 v[4:7], v[160:163], v[202:205], v[4:7]
	v_mfma_f32_16x16x32_bf16 v[0:3], v[168:171], v[202:205], v[0:3]
	v_mfma_f32_16x16x32_bf16 v[44:47], v[164:167], v[182:185], v[44:47]
	v_mfma_f32_16x16x32_bf16 v[40:43], v[172:175], v[182:185], v[40:43]
	v_mfma_f32_16x16x32_bf16 v[28:31], v[164:167], v[190:193], v[28:31]
	v_mfma_f32_16x16x32_bf16 v[24:27], v[172:175], v[190:193], v[24:27]
	v_mfma_f32_16x16x32_bf16 v[12:15], v[164:167], v[198:201], v[12:15]
	v_mfma_f32_16x16x32_bf16 v[8:11], v[172:175], v[198:201], v[8:11]
	v_mfma_f32_16x16x32_bf16 v[4:7], v[164:167], v[206:209], v[4:7]
	v_mfma_f32_16x16x32_bf16 v[0:3], v[172:175], v[206:209], v[0:3]
	s_barrier
	s_setprio 0
	s_add_i32 s49, s49, 2
	s_add_u32 s18, s18, 0x100
	s_addc_u32 s19, s19, 0
	s_add_u32 s50, s50, 0x100
	s_addc_u32 s48, s48, 0
	s_cmp_gt_u32 s49, 29
	s_cbranch_scc0 .LBB0_673
	s_and_b64 vcc, exec, s[6:7]
	s_cbranch_vccz .LBB0_676
	s_barrier

.LBB0_1261:
	s_add_i32 s97, s26, 2
	s_add_u32 s24, s22, 0x100
	s_addc_u32 s25, s23, 0
	s_add_i32 s88, 0, 0x10000
	s_cmp_eq_u32 s48, s26
	s_cselect_b32 s29, s11, s25
	s_cselect_b32 s28, vcc_lo, s24
	s_cselect_b32 s27, s9, s96
	s_cselect_b32 s26, vcc_hi, s49
	s_add_i32 s89, 0, 0x14000
	v_add_u32_e32 v140, s88, v160
	v_add_u32_e32 v166, s89, v160
	ds_read_b128 v[128:131], v140
	ds_read_b128 v[132:135], v140 offset:1024
	ds_read_b128 v[136:139], v140 offset:2048
	ds_read_b128 v[140:143], v140 offset:3072
	ds_read_b128 v[150:153], v166
	ds_read_b128 v[154:157], v166 offset:1024
	ds_read_b128 v[162:165], v166 offset:2048
	ds_read_b128 v[166:169], v166 offset:3072
	v_lshl_add_u64 v[174:175], s[22:23], 0, v[146:147]
	s_add_i32 m0, s35, 0xc000
	ds_read_b128 v[170:173], v161
	ds_read_b128 v[178:181], v161 offset:1024
	ds_read_b128 v[182:185], v161 offset:2048
	ds_read_b128 v[186:189], v161 offset:3072
	ds_read_b128 v[190:193], v161 offset:4096
	ds_read_b128 v[194:197], v161 offset:5120
	ds_read_b128 v[198:201], v161 offset:6144
	ds_read_b128 v[202:205], v161 offset:7168
	global_load_lds_dwordx4 v[174:175], off
	v_lshl_add_u64 v[174:175], s[22:23], 0, v[148:149]
	s_add_i32 m0, s35, 0xe000
	s_nop 0
	global_load_lds_dwordx4 v[174:175], off
	s_waitcnt vmcnt(8)
	s_waitcnt lgkmcnt(0)
	s_setprio 1
	s_barrier
	v_mfma_f32_16x16x32_bf16 v[124:127], v[128:131], v[170:173], v[124:127]
	v_mfma_f32_16x16x32_bf16 v[120:123], v[136:139], v[170:173], v[120:123]
	v_mfma_f32_16x16x32_bf16 v[112:115], v[128:131], v[182:185], v[112:115]
	v_mfma_f32_16x16x32_bf16 v[108:111], v[136:139], v[182:185], v[108:111]
	v_mfma_f32_16x16x32_bf16 v[100:103], v[128:131], v[190:193], v[100:103]
	v_mfma_f32_16x16x32_bf16 v[92:95], v[136:139], v[190:193], v[92:95]
	v_mfma_f32_16x16x32_bf16 v[84:87], v[128:131], v[198:201], v[84:87]
	v_mfma_f32_16x16x32_bf16 v[76:79], v[136:139], v[198:201], v[76:79]
	v_mfma_f32_16x16x32_bf16 v[124:127], v[132:135], v[178:181], v[124:127]
	v_mfma_f32_16x16x32_bf16 v[120:123], v[140:143], v[178:181], v[120:123]
	v_mfma_f32_16x16x32_bf16 v[112:115], v[132:135], v[186:189], v[112:115]
	v_mfma_f32_16x16x32_bf16 v[108:111], v[140:143], v[186:189], v[108:111]
	v_mfma_f32_16x16x32_bf16 v[100:103], v[132:135], v[194:197], v[100:103]
	v_mfma_f32_16x16x32_bf16 v[92:95], v[140:143], v[194:197], v[92:95]
	v_mfma_f32_16x16x32_bf16 v[84:87], v[132:135], v[202:205], v[84:87]
	v_mfma_f32_16x16x32_bf16 v[76:79], v[140:143], v[202:205], v[76:79]
	s_setprio 0
	s_setprio 1
	v_mfma_f32_16x16x32_bf16 v[116:119], v[150:153], v[170:173], v[116:119]
	v_mfma_f32_16x16x32_bf16 v[104:107], v[162:165], v[170:173], v[104:107]
	v_mfma_f32_16x16x32_bf16 v[96:99], v[150:153], v[182:185], v[96:99]
	v_mfma_f32_16x16x32_bf16 v[88:91], v[162:165], v[182:185], v[88:91]
	v_mfma_f32_16x16x32_bf16 v[80:83], v[150:153], v[190:193], v[80:83]
	v_mfma_f32_16x16x32_bf16 v[72:75], v[162:165], v[190:193], v[72:75]
	v_mfma_f32_16x16x32_bf16 v[68:71], v[150:153], v[198:201], v[68:71]
	v_mfma_f32_16x16x32_bf16 v[64:67], v[162:165], v[198:201], v[64:67]
	v_mfma_f32_16x16x32_bf16 v[116:119], v[154:157], v[178:181], v[116:119]
	v_mfma_f32_16x16x32_bf16 v[104:107], v[166:169], v[178:181], v[104:107]
	v_mfma_f32_16x16x32_bf16 v[96:99], v[154:157], v[186:189], v[96:99]
	v_mfma_f32_16x16x32_bf16 v[88:91], v[166:169], v[186:189], v[88:91]
	v_mfma_f32_16x16x32_bf16 v[80:83], v[154:157], v[194:197], v[80:83]
	v_mfma_f32_16x16x32_bf16 v[72:75], v[166:169], v[194:197], v[72:75]
	v_mfma_f32_16x16x32_bf16 v[68:71], v[154:157], v[202:205], v[68:71]
	v_mfma_f32_16x16x32_bf16 v[64:67], v[166:169], v[202:205], v[64:67]
	s_barrier
	s_setprio 0
	s_add_i32 s22, s88, s34
	v_lshl_add_u64 v[174:175], s[26:27], 0, v[176:177]
	s_mov_b32 m0, s22
	ds_read_b128 v[170:173], v161 offset:16384
	ds_read_b128 v[178:181], v161 offset:17408
	ds_read_b128 v[182:185], v161 offset:18432
	ds_read_b128 v[186:189], v161 offset:19456
	ds_read_b128 v[190:193], v161 offset:20480
	ds_read_b128 v[194:197], v161 offset:21504
	ds_read_b128 v[198:201], v161 offset:22528
	ds_read_b128 v[202:205], v161 offset:23552
	global_load_lds_dwordx4 v[174:175], off
	s_add_i32 m0, s22, 0x2000
	s_add_u32 s22, s26, 0x80000
	v_lshl_add_u64 v[206:207], s[26:27], 0, v[144:145]
	s_addc_u32 s23, s27, 0
	s_add_i32 s88, s89, s34
	global_load_lds_dwordx4 v[206:207], off
	v_lshl_add_u64 v[208:209], s[22:23], 0, v[176:177]
	s_mov_b32 m0, s88
	v_lshl_add_u64 v[210:211], s[28:29], 0, v[144:145]
	global_load_lds_dwordx4 v[208:209], off
	v_lshl_add_u64 v[208:209], s[22:23], 0, v[144:145]
	s_add_i32 m0, s88, 0x2000
	s_nop 0
	global_load_lds_dwordx4 v[208:209], off
	v_lshl_add_u64 v[208:209], s[28:29], 0, v[176:177]
	s_mov_b32 m0, s35
	s_nop 0
	global_load_lds_dwordx4 v[208:209], off
	s_mov_b32 m0, s36
	s_nop 0
	global_load_lds_dwordx4 v[210:211], off
	s_waitcnt vmcnt(8)
	s_waitcnt lgkmcnt(0)
	s_setprio 1
	s_barrier
	v_mfma_f32_16x16x32_bf16 v[60:63], v[128:131], v[170:173], v[60:63]
	v_mfma_f32_16x16x32_bf16 v[56:59], v[136:139], v[170:173], v[56:59]
	v_mfma_f32_16x16x32_bf16 v[52:55], v[128:131], v[182:185], v[52:55]
	v_mfma_f32_16x16x32_bf16 v[44:47], v[136:139], v[182:185], v[44:47]
	v_mfma_f32_16x16x32_bf16 v[36:39], v[128:131], v[190:193], v[36:39]
	v_mfma_f32_16x16x32_bf16 v[28:31], v[136:139], v[190:193], v[28:31]
	v_mfma_f32_16x16x32_bf16 v[16:19], v[128:131], v[198:201], v[16:19]
	v_mfma_f32_16x16x32_bf16 v[8:11], v[136:139], v[198:201], v[8:11]
	v_mfma_f32_16x16x32_bf16 v[60:63], v[132:135], v[178:181], v[60:63]
	v_mfma_f32_16x16x32_bf16 v[56:59], v[140:143], v[178:181], v[56:59]
	v_mfma_f32_16x16x32_bf16 v[52:55], v[132:135], v[186:189], v[52:55]
	v_mfma_f32_16x16x32_bf16 v[44:47], v[140:143], v[186:189], v[44:47]
	v_mfma_f32_16x16x32_bf16 v[36:39], v[132:135], v[194:197], v[36:39]
	v_mfma_f32_16x16x32_bf16 v[28:31], v[140:143], v[194:197], v[28:31]
	v_mfma_f32_16x16x32_bf16 v[16:19], v[132:135], v[202:205], v[16:19]
	v_mfma_f32_16x16x32_bf16 v[8:11], v[140:143], v[202:205], v[8:11]
	s_setprio 0
	s_setprio 1
	v_mfma_f32_16x16x32_bf16 v[48:51], v[150:153], v[170:173], v[48:51]
	v_mfma_f32_16x16x32_bf16 v[40:43], v[162:165], v[170:173], v[40:43]
	v_mfma_f32_16x16x32_bf16 v[32:35], v[150:153], v[182:185], v[32:35]
	v_mfma_f32_16x16x32_bf16 v[24:27], v[162:165], v[182:185], v[24:27]
	v_mfma_f32_16x16x32_bf16 v[20:23], v[150:153], v[190:193], v[20:23]
	v_mfma_f32_16x16x32_bf16 v[12:15], v[162:165], v[190:193], v[12:15]
	v_mfma_f32_16x16x32_bf16 v[4:7], v[150:153], v[198:201], v[4:7]
	v_mfma_f32_16x16x32_bf16 v[0:3], v[162:165], v[198:201], v[0:3]
	v_mfma_f32_16x16x32_bf16 v[48:51], v[154:157], v[178:181], v[48:51]
	v_mfma_f32_16x16x32_bf16 v[40:43], v[166:169], v[178:181], v[40:43]
	v_mfma_f32_16x16x32_bf16 v[32:35], v[154:157], v[186:189], v[32:35]
	v_mfma_f32_16x16x32_bf16 v[24:27], v[166:169], v[186:189], v[24:27]
	v_mfma_f32_16x16x32_bf16 v[20:23], v[154:157], v[194:197], v[20:23]
	v_mfma_f32_16x16x32_bf16 v[12:15], v[166:169], v[194:197], v[12:15]
	v_mfma_f32_16x16x32_bf16 v[4:7], v[154:157], v[202:205], v[4:7]
	v_mfma_f32_16x16x32_bf16 v[0:3], v[166:169], v[202:205], v[0:3]
	s_barrier
	s_setprio 0
	s_add_i32 s88, 0, 0x18000
	s_add_i32 s89, 0, 0x1c000
	v_add_u32_e32 v140, s88, v160
	v_add_u32_e32 v166, s89, v160
	ds_read_b128 v[128:131], v140
	ds_read_b128 v[132:135], v140 offset:1024
	ds_read_b128 v[136:139], v140 offset:2048
	ds_read_b128 v[140:143], v140 offset:3072
	ds_read_b128 v[150:153], v166
	ds_read_b128 v[154:157], v166 offset:1024
	ds_read_b128 v[162:165], v166 offset:2048
	ds_read_b128 v[166:169], v166 offset:3072
	s_add_u32 s22, s28, 0x80000
	s_addc_u32 s23, s29, 0
	s_mov_b32 m0, s37
	v_lshl_add_u64 v[212:213], s[22:23], 0, v[176:177]
	ds_read_b128 v[170:173], v161 offset:32768
	ds_read_b128 v[178:181], v161 offset:33792
	ds_read_b128 v[182:185], v161 offset:34816
	ds_read_b128 v[186:189], v161 offset:35840
	ds_read_b128 v[190:193], v161 offset:36864
	ds_read_b128 v[194:197], v161 offset:37888
	ds_read_b128 v[198:201], v161 offset:38912
	ds_read_b128 v[202:205], v161 offset:39936
	global_load_lds_dwordx4 v[212:213], off
	v_lshl_add_u64 v[212:213], s[22:23], 0, v[144:145]
	s_mov_b32 m0, s72
	s_nop 0
	global_load_lds_dwordx4 v[212:213], off
	s_waitcnt vmcnt(8)
	s_waitcnt lgkmcnt(0)
	s_setprio 1
	s_barrier
	v_mfma_f32_16x16x32_bf16 v[124:127], v[128:131], v[170:173], v[124:127]
	v_mfma_f32_16x16x32_bf16 v[120:123], v[136:139], v[170:173], v[120:123]
	v_mfma_f32_16x16x32_bf16 v[112:115], v[128:131], v[182:185], v[112:115]
	v_mfma_f32_16x16x32_bf16 v[108:111], v[136:139], v[182:185], v[108:111]
	v_mfma_f32_16x16x32_bf16 v[100:103], v[128:131], v[190:193], v[100:103]
	v_mfma_f32_16x16x32_bf16 v[92:95], v[136:139], v[190:193], v[92:95]
	v_mfma_f32_16x16x32_bf16 v[84:87], v[128:131], v[198:201], v[84:87]
	v_mfma_f32_16x16x32_bf16 v[76:79], v[136:139], v[198:201], v[76:79]
	v_mfma_f32_16x16x32_bf16 v[124:127], v[132:135], v[178:181], v[124:127]
	v_mfma_f32_16x16x32_bf16 v[120:123], v[140:143], v[178:181], v[120:123]
	v_mfma_f32_16x16x32_bf16 v[112:115], v[132:135], v[186:189], v[112:115]
	v_mfma_f32_16x16x32_bf16 v[108:111], v[140:143], v[186:189], v[108:111]
	v_mfma_f32_16x16x32_bf16 v[100:103], v[132:135], v[194:197], v[100:103]
	v_mfma_f32_16x16x32_bf16 v[92:95], v[140:143], v[194:197], v[92:95]
	v_mfma_f32_16x16x32_bf16 v[84:87], v[132:135], v[202:205], v[84:87]
	v_mfma_f32_16x16x32_bf16 v[76:79], v[140:143], v[202:205], v[76:79]
	s_setprio 0
	s_setprio 1
	v_mfma_f32_16x16x32_bf16 v[116:119], v[150:153], v[170:173], v[116:119]
	v_mfma_f32_16x16x32_bf16 v[104:107], v[162:165], v[170:173], v[104:107]
	v_mfma_f32_16x16x32_bf16 v[96:99], v[150:153], v[182:185], v[96:99]
	v_mfma_f32_16x16x32_bf16 v[88:91], v[162:165], v[182:185], v[88:91]
	v_mfma_f32_16x16x32_bf16 v[80:83], v[150:153], v[190:193], v[80:83]
	v_mfma_f32_16x16x32_bf16 v[72:75], v[162:165], v[190:193], v[72:75]
	v_mfma_f32_16x16x32_bf16 v[68:71], v[150:153], v[198:201], v[68:71]
	v_mfma_f32_16x16x32_bf16 v[64:67], v[162:165], v[198:201], v[64:67]
	v_mfma_f32_16x16x32_bf16 v[116:119], v[154:157], v[178:181], v[116:119]
	v_mfma_f32_16x16x32_bf16 v[104:107], v[166:169], v[178:181], v[104:107]
	v_mfma_f32_16x16x32_bf16 v[96:99], v[154:157], v[186:189], v[96:99]
	v_mfma_f32_16x16x32_bf16 v[88:91], v[166:169], v[186:189], v[88:91]
	v_mfma_f32_16x16x32_bf16 v[80:83], v[154:157], v[194:197], v[80:83]
	v_mfma_f32_16x16x32_bf16 v[72:75], v[166:169], v[194:197], v[72:75]
	v_mfma_f32_16x16x32_bf16 v[68:71], v[154:157], v[202:205], v[68:71]
	v_mfma_f32_16x16x32_bf16 v[64:67], v[166:169], v[202:205], v[64:67]
	s_barrier
	s_setprio 0
	s_add_i32 s22, s88, s34
	v_lshl_add_u64 v[174:175], v[174:175], 0, s[40:41]
	s_mov_b32 m0, s22
	ds_read_b128 v[170:173], v161 offset:49152
	ds_read_b128 v[178:181], v161 offset:50176
	ds_read_b128 v[182:185], v161 offset:51200
	ds_read_b128 v[186:189], v161 offset:52224
	ds_read_b128 v[190:193], v161 offset:53248
	ds_read_b128 v[194:197], v161 offset:54272
	ds_read_b128 v[198:201], v161 offset:55296
	ds_read_b128 v[202:205], v161 offset:56320
	global_load_lds_dwordx4 v[174:175], off
	s_add_i32 m0, s22, 0x2000
	s_add_u32 s22, s26, 0x80080
	v_lshl_add_u64 v[174:175], v[206:207], 0, s[40:41]
	s_addc_u32 s23, s27, 0
	s_add_i32 s26, s89, s34
	global_load_lds_dwordx4 v[174:175], off
	v_lshl_add_u64 v[174:175], s[22:23], 0, v[176:177]
	s_mov_b32 m0, s26
	s_nop 0
	global_load_lds_dwordx4 v[174:175], off
	v_lshl_add_u64 v[174:175], s[22:23], 0, v[144:145]
	s_add_i32 m0, s26, 0x2000
	s_nop 0
	global_load_lds_dwordx4 v[174:175], off
	v_lshl_add_u64 v[174:175], v[208:209], 0, s[40:41]
	s_mov_b32 m0, s46
	s_nop 0
	global_load_lds_dwordx4 v[174:175], off
	v_lshl_add_u64 v[174:175], v[210:211], 0, s[40:41]
	s_mov_b32 m0, s47
	s_nop 0
	global_load_lds_dwordx4 v[174:175], off
	s_waitcnt vmcnt(8)
	s_waitcnt lgkmcnt(0)
	s_setprio 1
	s_barrier
	v_mfma_f32_16x16x32_bf16 v[60:63], v[128:131], v[170:173], v[60:63]
	v_mfma_f32_16x16x32_bf16 v[56:59], v[136:139], v[170:173], v[56:59]
	v_mfma_f32_16x16x32_bf16 v[52:55], v[128:131], v[182:185], v[52:55]
	v_mfma_f32_16x16x32_bf16 v[44:47], v[136:139], v[182:185], v[44:47]
	v_mfma_f32_16x16x32_bf16 v[36:39], v[128:131], v[190:193], v[36:39]
	v_mfma_f32_16x16x32_bf16 v[28:31], v[136:139], v[190:193], v[28:31]
	v_mfma_f32_16x16x32_bf16 v[16:19], v[128:131], v[198:201], v[16:19]
	v_mfma_f32_16x16x32_bf16 v[8:11], v[136:139], v[198:201], v[8:11]
	v_mfma_f32_16x16x32_bf16 v[60:63], v[132:135], v[178:181], v[60:63]
	v_mfma_f32_16x16x32_bf16 v[56:59], v[140:143], v[178:181], v[56:59]
	v_mfma_f32_16x16x32_bf16 v[52:55], v[132:135], v[186:189], v[52:55]
	v_mfma_f32_16x16x32_bf16 v[44:47], v[140:143], v[186:189], v[44:47]
	v_mfma_f32_16x16x32_bf16 v[36:39], v[132:135], v[194:197], v[36:39]
	v_mfma_f32_16x16x32_bf16 v[28:31], v[140:143], v[194:197], v[28:31]
	v_mfma_f32_16x16x32_bf16 v[16:19], v[132:135], v[202:205], v[16:19]
	v_mfma_f32_16x16x32_bf16 v[8:11], v[140:143], v[202:205], v[8:11]
	s_setprio 0
	s_setprio 1
	v_mfma_f32_16x16x32_bf16 v[48:51], v[150:153], v[170:173], v[48:51]
	v_mfma_f32_16x16x32_bf16 v[40:43], v[162:165], v[170:173], v[40:43]
	v_mfma_f32_16x16x32_bf16 v[32:35], v[150:153], v[182:185], v[32:35]
	v_mfma_f32_16x16x32_bf16 v[24:27], v[162:165], v[182:185], v[24:27]
	v_mfma_f32_16x16x32_bf16 v[20:23], v[150:153], v[190:193], v[20:23]
	v_mfma_f32_16x16x32_bf16 v[12:15], v[162:165], v[190:193], v[12:15]
	v_mfma_f32_16x16x32_bf16 v[4:7], v[150:153], v[198:201], v[4:7]
	v_mfma_f32_16x16x32_bf16 v[0:3], v[162:165], v[198:201], v[0:3]
	v_mfma_f32_16x16x32_bf16 v[48:51], v[154:157], v[178:181], v[48:51]
	v_mfma_f32_16x16x32_bf16 v[40:43], v[166:169], v[178:181], v[40:43]
	v_mfma_f32_16x16x32_bf16 v[32:35], v[154:157], v[186:189], v[32:35]
	v_mfma_f32_16x16x32_bf16 v[24:27], v[166:169], v[186:189], v[24:27]
	v_mfma_f32_16x16x32_bf16 v[20:23], v[154:157], v[194:197], v[20:23]
	v_mfma_f32_16x16x32_bf16 v[12:15], v[166:169], v[194:197], v[12:15]
	v_mfma_f32_16x16x32_bf16 v[4:7], v[154:157], v[202:205], v[4:7]
	v_mfma_f32_16x16x32_bf16 v[0:3], v[166:169], v[202:205], v[0:3]
	s_barrier
	s_setprio 0
	s_add_u32 s49, s49, 0x100
	s_addc_u32 s96, s96, 0
	s_cmp_ge_u32 s97, s7
	s_mov_b64 s[22:23], s[24:25]
	s_mov_b32 s26, s97
	s_cbranch_scc0 .LBB0_1261
	s_and_b64 vcc, exec, s[4:5]
	s_cbranch_vccz .LBB0_1264
	s_barrier

.LBB0_1383:
	s_add_u32 s34, s10, 0xfff80080
	s_addc_u32 s35, s11, -1
	s_add_i32 s88, 0, 0x10000
	s_cmp_eq_u32 s49, 28
	s_cselect_b32 s47, s7, s35
	s_cselect_b32 s46, s25, s34
	s_cselect_b32 s35, s23, s48
	s_cselect_b32 s34, vcc_lo, vcc_hi
	s_add_i32 s89, 0, 0x14000
	v_add_u32_e32 v140, s88, v240
	v_add_u32_e32 v156, s89, v240
	ds_read_b128 v[128:131], v140
	ds_read_b128 v[132:135], v140 offset:1024
	ds_read_b128 v[136:139], v140 offset:2048
	ds_read_b128 v[140:143], v140 offset:3072
	ds_read_b128 v[144:147], v156
	ds_read_b128 v[148:151], v156 offset:1024
	ds_read_b128 v[152:155], v156 offset:2048
	ds_read_b128 v[156:159], v156 offset:3072
	v_lshl_add_u64 v[212:213], s[10:11], 0, v[184:185]
	s_add_i32 m0, s31, 0xc000
	ds_read_b128 v[188:191], v241
	ds_read_b128 v[192:195], v241 offset:1024
	ds_read_b128 v[196:199], v241 offset:2048
	ds_read_b128 v[200:203], v241 offset:3072
	ds_read_b128 v[204:207], v241 offset:4096
	ds_read_b128 v[208:211], v241 offset:5120
	ds_read_b128 v[220:223], v241 offset:6144
	ds_read_b128 v[242:245], v241 offset:7168
	global_load_lds_dwordx4 v[212:213], off
	v_lshl_add_u64 v[212:213], s[10:11], 0, v[186:187]
	s_add_i32 m0, s31, 0xe000
	s_nop 0
	global_load_lds_dwordx4 v[212:213], off
	s_waitcnt vmcnt(8)
	s_waitcnt lgkmcnt(0)
	s_setprio 1
	s_barrier
	v_mfma_f32_16x16x32_bf16 v[116:119], v[128:131], v[188:191], v[116:119]
	v_mfma_f32_16x16x32_bf16 v[84:87], v[136:139], v[188:191], v[84:87]
	v_mfma_f32_16x16x32_bf16 v[124:127], v[128:131], v[196:199], v[124:127]
	v_mfma_f32_16x16x32_bf16 v[108:111], v[136:139], v[196:199], v[108:111]
	v_mfma_f32_16x16x32_bf16 v[120:123], v[128:131], v[204:207], v[120:123]
	v_mfma_f32_16x16x32_bf16 v[92:95], v[136:139], v[204:207], v[92:95]
	v_mfma_f32_16x16x32_bf16 v[112:115], v[128:131], v[220:223], v[112:115]
	v_mfma_f32_16x16x32_bf16 v[80:83], v[136:139], v[220:223], v[80:83]
	v_mfma_f32_16x16x32_bf16 v[116:119], v[132:135], v[192:195], v[116:119]
	v_mfma_f32_16x16x32_bf16 v[84:87], v[140:143], v[192:195], v[84:87]
	v_mfma_f32_16x16x32_bf16 v[124:127], v[132:135], v[200:203], v[124:127]
	v_mfma_f32_16x16x32_bf16 v[108:111], v[140:143], v[200:203], v[108:111]
	v_mfma_f32_16x16x32_bf16 v[120:123], v[132:135], v[208:211], v[120:123]
	v_mfma_f32_16x16x32_bf16 v[92:95], v[140:143], v[208:211], v[92:95]
	v_mfma_f32_16x16x32_bf16 v[112:115], v[132:135], v[242:245], v[112:115]
	v_mfma_f32_16x16x32_bf16 v[80:83], v[140:143], v[242:245], v[80:83]
	s_setprio 0
	s_setprio 1
	v_mfma_f32_16x16x32_bf16 v[52:55], v[144:147], v[188:191], v[52:55]
	v_mfma_f32_16x16x32_bf16 v[20:23], v[152:155], v[188:191], v[20:23]
	v_mfma_f32_16x16x32_bf16 v[60:63], v[144:147], v[196:199], v[60:63]
	v_mfma_f32_16x16x32_bf16 v[28:31], v[152:155], v[196:199], v[28:31]
	v_mfma_f32_16x16x32_bf16 v[56:59], v[144:147], v[204:207], v[56:59]
	v_mfma_f32_16x16x32_bf16 v[24:27], v[152:155], v[204:207], v[24:27]
	v_mfma_f32_16x16x32_bf16 v[48:51], v[144:147], v[220:223], v[48:51]
	v_mfma_f32_16x16x32_bf16 v[16:19], v[152:155], v[220:223], v[16:19]
	v_mfma_f32_16x16x32_bf16 v[52:55], v[148:151], v[192:195], v[52:55]
	v_mfma_f32_16x16x32_bf16 v[20:23], v[156:159], v[192:195], v[20:23]
	v_mfma_f32_16x16x32_bf16 v[60:63], v[148:151], v[200:203], v[60:63]
	v_mfma_f32_16x16x32_bf16 v[28:31], v[156:159], v[200:203], v[28:31]
	v_mfma_f32_16x16x32_bf16 v[56:59], v[148:151], v[208:211], v[56:59]
	v_mfma_f32_16x16x32_bf16 v[24:27], v[156:159], v[208:211], v[24:27]
	v_mfma_f32_16x16x32_bf16 v[48:51], v[148:151], v[242:245], v[48:51]
	v_mfma_f32_16x16x32_bf16 v[16:19], v[156:159], v[242:245], v[16:19]
	s_barrier
	s_setprio 0
	s_add_i32 s88, s88, s37
	v_lshl_add_u64 v[212:213], s[34:35], 0, v[176:177]
	s_mov_b32 m0, s88
	ds_read_b128 v[188:191], v241 offset:16384
	ds_read_b128 v[192:195], v241 offset:17408
	ds_read_b128 v[196:199], v241 offset:18432
	ds_read_b128 v[200:203], v241 offset:19456
	ds_read_b128 v[204:207], v241 offset:20480
	ds_read_b128 v[208:211], v241 offset:21504
	ds_read_b128 v[220:223], v241 offset:22528
	ds_read_b128 v[242:245], v241 offset:23552
	global_load_lds_dwordx4 v[212:213], off
	s_add_i32 m0, s88, 0x2000
	s_add_u32 s96, s34, 0x80000
	v_lshl_add_u64 v[224:225], s[34:35], 0, v[164:165]
	s_addc_u32 s97, s35, 0
	s_add_i32 s88, s89, s37
	global_load_lds_dwordx4 v[224:225], off
	v_lshl_add_u64 v[228:229], s[96:97], 0, v[176:177]
	s_mov_b32 m0, s88
	v_lshl_add_u64 v[246:247], s[46:47], 0, v[162:163]
	global_load_lds_dwordx4 v[228:229], off
	v_lshl_add_u64 v[228:229], s[96:97], 0, v[164:165]
	s_add_i32 m0, s88, 0x2000
	s_nop 0
	global_load_lds_dwordx4 v[228:229], off
	v_lshl_add_u64 v[228:229], s[46:47], 0, v[160:161]
	s_mov_b32 m0, s31
	s_nop 0
	global_load_lds_dwordx4 v[228:229], off
	s_mov_b32 m0, s8
	s_nop 0
	global_load_lds_dwordx4 v[246:247], off
	s_waitcnt vmcnt(8)
	s_waitcnt lgkmcnt(0)
	s_setprio 1
	s_barrier
	v_mfma_f32_16x16x32_bf16 v[100:103], v[128:131], v[188:191], v[100:103]
	v_mfma_f32_16x16x32_bf16 v[72:75], v[136:139], v[188:191], v[72:75]
	v_mfma_f32_16x16x32_bf16 v[104:107], v[128:131], v[196:199], v[104:107]
	v_mfma_f32_16x16x32_bf16 v[76:79], v[136:139], v[196:199], v[76:79]
	v_mfma_f32_16x16x32_bf16 v[96:99], v[128:131], v[204:207], v[96:99]
	v_mfma_f32_16x16x32_bf16 v[68:71], v[136:139], v[204:207], v[68:71]
	v_mfma_f32_16x16x32_bf16 v[88:91], v[128:131], v[220:223], v[88:91]
	v_mfma_f32_16x16x32_bf16 v[64:67], v[136:139], v[220:223], v[64:67]
	v_mfma_f32_16x16x32_bf16 v[100:103], v[132:135], v[192:195], v[100:103]
	v_mfma_f32_16x16x32_bf16 v[72:75], v[140:143], v[192:195], v[72:75]
	v_mfma_f32_16x16x32_bf16 v[104:107], v[132:135], v[200:203], v[104:107]
	v_mfma_f32_16x16x32_bf16 v[76:79], v[140:143], v[200:203], v[76:79]
	v_mfma_f32_16x16x32_bf16 v[96:99], v[132:135], v[208:211], v[96:99]
	v_mfma_f32_16x16x32_bf16 v[68:71], v[140:143], v[208:211], v[68:71]
	v_mfma_f32_16x16x32_bf16 v[88:91], v[132:135], v[242:245], v[88:91]
	v_mfma_f32_16x16x32_bf16 v[64:67], v[140:143], v[242:245], v[64:67]
	s_setprio 0
	s_setprio 1
	v_mfma_f32_16x16x32_bf16 v[44:47], v[144:147], v[188:191], v[44:47]
	v_mfma_f32_16x16x32_bf16 v[8:11], v[152:155], v[188:191], v[8:11]
	v_mfma_f32_16x16x32_bf16 v[40:43], v[144:147], v[196:199], v[40:43]
	v_mfma_f32_16x16x32_bf16 v[12:15], v[152:155], v[196:199], v[12:15]
	v_mfma_f32_16x16x32_bf16 v[36:39], v[144:147], v[204:207], v[36:39]
	v_mfma_f32_16x16x32_bf16 v[4:7], v[152:155], v[204:207], v[4:7]
	v_mfma_f32_16x16x32_bf16 v[32:35], v[144:147], v[220:223], v[32:35]
	v_mfma_f32_16x16x32_bf16 v[0:3], v[152:155], v[220:223], v[0:3]
	v_mfma_f32_16x16x32_bf16 v[44:47], v[148:151], v[192:195], v[44:47]
	v_mfma_f32_16x16x32_bf16 v[8:11], v[156:159], v[192:195], v[8:11]
	v_mfma_f32_16x16x32_bf16 v[40:43], v[148:151], v[200:203], v[40:43]
	v_mfma_f32_16x16x32_bf16 v[12:15], v[156:159], v[200:203], v[12:15]
	v_mfma_f32_16x16x32_bf16 v[36:39], v[148:151], v[208:211], v[36:39]
	v_mfma_f32_16x16x32_bf16 v[4:7], v[156:159], v[208:211], v[4:7]
	v_mfma_f32_16x16x32_bf16 v[32:35], v[148:151], v[242:245], v[32:35]
	v_mfma_f32_16x16x32_bf16 v[0:3], v[156:159], v[242:245], v[0:3]
	s_barrier
	s_setprio 0
	s_add_i32 s88, 0, 0x18000
	s_add_i32 s89, 0, 0x1c000
	v_add_u32_e32 v140, s88, v240
	v_add_u32_e32 v156, s89, v240
	ds_read_b128 v[128:131], v140
	ds_read_b128 v[132:135], v140 offset:1024
	ds_read_b128 v[136:139], v140 offset:2048
	ds_read_b128 v[140:143], v140 offset:3072
	ds_read_b128 v[144:147], v156
	ds_read_b128 v[148:151], v156 offset:1024
	ds_read_b128 v[152:155], v156 offset:2048
	ds_read_b128 v[156:159], v156 offset:3072
	s_add_u32 s46, s46, 0x80000
	s_addc_u32 s47, s47, 0
	s_mov_b32 m0, s9
	v_lshl_add_u64 v[248:249], s[46:47], 0, v[160:161]
	ds_read_b128 v[188:191], v241 offset:32768
	ds_read_b128 v[192:195], v241 offset:33792
	ds_read_b128 v[196:199], v241 offset:34816
	ds_read_b128 v[200:203], v241 offset:35840
	ds_read_b128 v[204:207], v241 offset:36864
	ds_read_b128 v[208:211], v241 offset:37888
	ds_read_b128 v[220:223], v241 offset:38912
	ds_read_b128 v[242:245], v241 offset:39936
	global_load_lds_dwordx4 v[248:249], off
	v_lshl_add_u64 v[248:249], s[46:47], 0, v[162:163]
	s_mov_b32 m0, s92
	s_nop 0
	global_load_lds_dwordx4 v[248:249], off
	s_waitcnt vmcnt(8)
	s_waitcnt lgkmcnt(0)
	s_setprio 1
	s_barrier
	v_mfma_f32_16x16x32_bf16 v[116:119], v[128:131], v[188:191], v[116:119]
	v_mfma_f32_16x16x32_bf16 v[84:87], v[136:139], v[188:191], v[84:87]
	v_mfma_f32_16x16x32_bf16 v[124:127], v[128:131], v[196:199], v[124:127]
	v_mfma_f32_16x16x32_bf16 v[108:111], v[136:139], v[196:199], v[108:111]
	v_mfma_f32_16x16x32_bf16 v[120:123], v[128:131], v[204:207], v[120:123]
	v_mfma_f32_16x16x32_bf16 v[92:95], v[136:139], v[204:207], v[92:95]
	v_mfma_f32_16x16x32_bf16 v[112:115], v[128:131], v[220:223], v[112:115]
	v_mfma_f32_16x16x32_bf16 v[80:83], v[136:139], v[220:223], v[80:83]
	v_mfma_f32_16x16x32_bf16 v[116:119], v[132:135], v[192:195], v[116:119]
	v_mfma_f32_16x16x32_bf16 v[84:87], v[140:143], v[192:195], v[84:87]
	v_mfma_f32_16x16x32_bf16 v[124:127], v[132:135], v[200:203], v[124:127]
	v_mfma_f32_16x16x32_bf16 v[108:111], v[140:143], v[200:203], v[108:111]
	v_mfma_f32_16x16x32_bf16 v[120:123], v[132:135], v[208:211], v[120:123]
	v_mfma_f32_16x16x32_bf16 v[92:95], v[140:143], v[208:211], v[92:95]
	v_mfma_f32_16x16x32_bf16 v[112:115], v[132:135], v[242:245], v[112:115]
	v_mfma_f32_16x16x32_bf16 v[80:83], v[140:143], v[242:245], v[80:83]
	s_setprio 0
	s_setprio 1
	v_mfma_f32_16x16x32_bf16 v[52:55], v[144:147], v[188:191], v[52:55]
	v_mfma_f32_16x16x32_bf16 v[20:23], v[152:155], v[188:191], v[20:23]
	v_mfma_f32_16x16x32_bf16 v[60:63], v[144:147], v[196:199], v[60:63]
	v_mfma_f32_16x16x32_bf16 v[28:31], v[152:155], v[196:199], v[28:31]
	v_mfma_f32_16x16x32_bf16 v[56:59], v[144:147], v[204:207], v[56:59]
	v_mfma_f32_16x16x32_bf16 v[24:27], v[152:155], v[204:207], v[24:27]
	v_mfma_f32_16x16x32_bf16 v[48:51], v[144:147], v[220:223], v[48:51]
	v_mfma_f32_16x16x32_bf16 v[16:19], v[152:155], v[220:223], v[16:19]
	v_mfma_f32_16x16x32_bf16 v[52:55], v[148:151], v[192:195], v[52:55]
	v_mfma_f32_16x16x32_bf16 v[20:23], v[156:159], v[192:195], v[20:23]
	v_mfma_f32_16x16x32_bf16 v[60:63], v[148:151], v[200:203], v[60:63]
	v_mfma_f32_16x16x32_bf16 v[28:31], v[156:159], v[200:203], v[28:31]
	v_mfma_f32_16x16x32_bf16 v[56:59], v[148:151], v[208:211], v[56:59]
	v_mfma_f32_16x16x32_bf16 v[24:27], v[156:159], v[208:211], v[24:27]
	v_mfma_f32_16x16x32_bf16 v[48:51], v[148:151], v[242:245], v[48:51]
	v_mfma_f32_16x16x32_bf16 v[16:19], v[156:159], v[242:245], v[16:19]
	s_barrier
	s_setprio 0
	s_add_i32 s46, s88, s37
	v_lshl_add_u64 v[212:213], v[212:213], 0, s[40:41]
	s_mov_b32 m0, s46
	ds_read_b128 v[188:191], v241 offset:49152
	ds_read_b128 v[192:195], v241 offset:50176
	ds_read_b128 v[196:199], v241 offset:51200
	ds_read_b128 v[200:203], v241 offset:52224
	ds_read_b128 v[204:207], v241 offset:53248
	ds_read_b128 v[208:211], v241 offset:54272
	ds_read_b128 v[220:223], v241 offset:55296
	ds_read_b128 v[242:245], v241 offset:56320
	global_load_lds_dwordx4 v[212:213], off
	s_add_i32 m0, s46, 0x2000
	s_add_u32 s34, s34, 0x80080
	v_lshl_add_u64 v[212:213], v[224:225], 0, s[40:41]
	s_addc_u32 s35, s35, 0
	s_add_i32 s46, s89, s37
	global_load_lds_dwordx4 v[212:213], off
	v_lshl_add_u64 v[212:213], s[34:35], 0, v[176:177]
	s_mov_b32 m0, s46
	s_nop 0
	global_load_lds_dwordx4 v[212:213], off
	v_lshl_add_u64 v[212:213], s[34:35], 0, v[164:165]
	s_add_i32 m0, s46, 0x2000
	s_nop 0
	global_load_lds_dwordx4 v[212:213], off
	v_lshl_add_u64 v[212:213], v[228:229], 0, s[40:41]
	s_mov_b32 m0, s56
	s_nop 0
	global_load_lds_dwordx4 v[212:213], off
	v_lshl_add_u64 v[212:213], v[246:247], 0, s[40:41]
	s_mov_b32 m0, s57
	s_nop 0
	global_load_lds_dwordx4 v[212:213], off
	s_waitcnt vmcnt(8)
	s_waitcnt lgkmcnt(0)
	s_setprio 1
	s_barrier
	v_mfma_f32_16x16x32_bf16 v[100:103], v[128:131], v[188:191], v[100:103]
	v_mfma_f32_16x16x32_bf16 v[72:75], v[136:139], v[188:191], v[72:75]
	v_mfma_f32_16x16x32_bf16 v[104:107], v[128:131], v[196:199], v[104:107]
	v_mfma_f32_16x16x32_bf16 v[76:79], v[136:139], v[196:199], v[76:79]
	v_mfma_f32_16x16x32_bf16 v[96:99], v[128:131], v[204:207], v[96:99]
	v_mfma_f32_16x16x32_bf16 v[68:71], v[136:139], v[204:207], v[68:71]
	v_mfma_f32_16x16x32_bf16 v[88:91], v[128:131], v[220:223], v[88:91]
	v_mfma_f32_16x16x32_bf16 v[64:67], v[136:139], v[220:223], v[64:67]
	v_mfma_f32_16x16x32_bf16 v[100:103], v[132:135], v[192:195], v[100:103]
	v_mfma_f32_16x16x32_bf16 v[72:75], v[140:143], v[192:195], v[72:75]
	v_mfma_f32_16x16x32_bf16 v[104:107], v[132:135], v[200:203], v[104:107]
	v_mfma_f32_16x16x32_bf16 v[76:79], v[140:143], v[200:203], v[76:79]
	v_mfma_f32_16x16x32_bf16 v[96:99], v[132:135], v[208:211], v[96:99]
	v_mfma_f32_16x16x32_bf16 v[68:71], v[140:143], v[208:211], v[68:71]
	v_mfma_f32_16x16x32_bf16 v[88:91], v[132:135], v[242:245], v[88:91]
	v_mfma_f32_16x16x32_bf16 v[64:67], v[140:143], v[242:245], v[64:67]
	s_setprio 0
	s_setprio 1
	v_mfma_f32_16x16x32_bf16 v[44:47], v[144:147], v[188:191], v[44:47]
	v_mfma_f32_16x16x32_bf16 v[8:11], v[152:155], v[188:191], v[8:11]
	v_mfma_f32_16x16x32_bf16 v[40:43], v[144:147], v[196:199], v[40:43]
	v_mfma_f32_16x16x32_bf16 v[12:15], v[152:155], v[196:199], v[12:15]
	v_mfma_f32_16x16x32_bf16 v[36:39], v[144:147], v[204:207], v[36:39]
	v_mfma_f32_16x16x32_bf16 v[4:7], v[152:155], v[204:207], v[4:7]
	v_mfma_f32_16x16x32_bf16 v[32:35], v[144:147], v[220:223], v[32:35]
	v_mfma_f32_16x16x32_bf16 v[0:3], v[152:155], v[220:223], v[0:3]
	v_mfma_f32_16x16x32_bf16 v[44:47], v[148:151], v[192:195], v[44:47]
	v_mfma_f32_16x16x32_bf16 v[8:11], v[156:159], v[192:195], v[8:11]
	v_mfma_f32_16x16x32_bf16 v[40:43], v[148:151], v[200:203], v[40:43]
	v_mfma_f32_16x16x32_bf16 v[12:15], v[156:159], v[200:203], v[12:15]
	v_mfma_f32_16x16x32_bf16 v[36:39], v[148:151], v[208:211], v[36:39]
	v_mfma_f32_16x16x32_bf16 v[4:7], v[156:159], v[208:211], v[4:7]
	v_mfma_f32_16x16x32_bf16 v[32:35], v[148:151], v[242:245], v[32:35]
	v_mfma_f32_16x16x32_bf16 v[0:3], v[156:159], v[242:245], v[0:3]
	s_barrier
	s_setprio 0
	s_add_i32 s49, s49, 2
	s_add_u32 s10, s10, 0x100
	s_addc_u32 s11, s11, 0
	s_add_u32 vcc_hi, vcc_hi, 0x100
	s_addc_u32 s48, s48, 0
	s_cmp_gt_u32 s49, 29
	s_cbranch_scc0 .LBB0_1383
	s_and_b64 vcc, exec, s[16:17]
	s_cbranch_vccz .LBB0_1386
	s_barrier

.LBB0_1801:
	s_add_i32 s97, s22, 2
	s_add_u32 s20, s18, 0x100
	s_addc_u32 s21, s19, 0
	s_add_i32 s88, 0, 0x10000
	s_cmp_eq_u32 s48, s22
	s_cselect_b32 s25, s15, s21
	s_cselect_b32 s24, s14, s20
	s_cselect_b32 s23, s17, s96
	s_cselect_b32 s22, s16, s49
	s_add_i32 s89, 0, 0x14000
	v_add_u32_e32 v140, s88, v158
	v_add_u32_e32 v154, s89, v158
	ds_read_b128 v[128:131], v140
	ds_read_b128 v[132:135], v140 offset:1024
	ds_read_b128 v[136:139], v140 offset:2048
	ds_read_b128 v[140:143], v140 offset:3072
	ds_read_b128 v[150:153], v154
	ds_read_b128 v[160:163], v154 offset:1024
	ds_read_b128 v[164:167], v154 offset:2048
	ds_read_b128 v[168:171], v154 offset:3072
	v_lshl_add_u64 v[154:155], s[18:19], 0, v[146:147]
	s_add_i32 m0, s28, 0xc000
	ds_read_b128 v[172:175], v159
	ds_read_b128 v[178:181], v159 offset:1024
	ds_read_b128 v[182:185], v159 offset:2048
	ds_read_b128 v[186:189], v159 offset:3072
	ds_read_b128 v[190:193], v159 offset:4096
	ds_read_b128 v[194:197], v159 offset:5120
	ds_read_b128 v[198:201], v159 offset:6144
	ds_read_b128 v[202:205], v159 offset:7168
	global_load_lds_dwordx4 v[154:155], off
	v_lshl_add_u64 v[154:155], s[18:19], 0, v[148:149]
	s_add_i32 m0, s28, 0xe000
	s_nop 0
	global_load_lds_dwordx4 v[154:155], off
	s_waitcnt vmcnt(8)
	s_waitcnt lgkmcnt(0)
	s_setprio 1
	s_barrier
	v_mfma_f32_16x16x32_bf16 v[124:127], v[128:131], v[172:175], v[124:127]
	v_mfma_f32_16x16x32_bf16 v[120:123], v[136:139], v[172:175], v[120:123]
	v_mfma_f32_16x16x32_bf16 v[116:119], v[128:131], v[182:185], v[116:119]
	v_mfma_f32_16x16x32_bf16 v[112:115], v[136:139], v[182:185], v[112:115]
	v_mfma_f32_16x16x32_bf16 v[108:111], v[128:131], v[190:193], v[108:111]
	v_mfma_f32_16x16x32_bf16 v[100:103], v[136:139], v[190:193], v[100:103]
	v_mfma_f32_16x16x32_bf16 v[92:95], v[128:131], v[198:201], v[92:95]
	v_mfma_f32_16x16x32_bf16 v[72:75], v[136:139], v[198:201], v[72:75]
	v_mfma_f32_16x16x32_bf16 v[124:127], v[132:135], v[178:181], v[124:127]
	v_mfma_f32_16x16x32_bf16 v[120:123], v[140:143], v[178:181], v[120:123]
	v_mfma_f32_16x16x32_bf16 v[116:119], v[132:135], v[186:189], v[116:119]
	v_mfma_f32_16x16x32_bf16 v[112:115], v[140:143], v[186:189], v[112:115]
	v_mfma_f32_16x16x32_bf16 v[108:111], v[132:135], v[194:197], v[108:111]
	v_mfma_f32_16x16x32_bf16 v[100:103], v[140:143], v[194:197], v[100:103]
	v_mfma_f32_16x16x32_bf16 v[92:95], v[132:135], v[202:205], v[92:95]
	v_mfma_f32_16x16x32_bf16 v[72:75], v[140:143], v[202:205], v[72:75]
	s_setprio 0
	s_setprio 1
	v_mfma_f32_16x16x32_bf16 v[104:107], v[150:153], v[172:175], v[104:107]
	v_mfma_f32_16x16x32_bf16 v[96:99], v[164:167], v[172:175], v[96:99]
	v_mfma_f32_16x16x32_bf16 v[88:91], v[150:153], v[182:185], v[88:91]
	v_mfma_f32_16x16x32_bf16 v[84:87], v[164:167], v[182:185], v[84:87]
	v_mfma_f32_16x16x32_bf16 v[80:83], v[150:153], v[190:193], v[80:83]
	v_mfma_f32_16x16x32_bf16 v[76:79], v[164:167], v[190:193], v[76:79]
	v_mfma_f32_16x16x32_bf16 v[68:71], v[150:153], v[198:201], v[68:71]
	v_mfma_f32_16x16x32_bf16 v[64:67], v[164:167], v[198:201], v[64:67]
	v_mfma_f32_16x16x32_bf16 v[104:107], v[160:163], v[178:181], v[104:107]
	v_mfma_f32_16x16x32_bf16 v[96:99], v[168:171], v[178:181], v[96:99]
	v_mfma_f32_16x16x32_bf16 v[88:91], v[160:163], v[186:189], v[88:91]
	v_mfma_f32_16x16x32_bf16 v[84:87], v[168:171], v[186:189], v[84:87]
	v_mfma_f32_16x16x32_bf16 v[80:83], v[160:163], v[194:197], v[80:83]
	v_mfma_f32_16x16x32_bf16 v[76:79], v[168:171], v[194:197], v[76:79]
	v_mfma_f32_16x16x32_bf16 v[68:71], v[160:163], v[202:205], v[68:71]
	v_mfma_f32_16x16x32_bf16 v[64:67], v[168:171], v[202:205], v[64:67]
	s_barrier
	s_setprio 0
	s_add_i32 s18, s88, s27
	v_lshl_add_u64 v[154:155], s[22:23], 0, v[176:177]
	s_mov_b32 m0, s18
	ds_read_b128 v[172:175], v159 offset:16384
	ds_read_b128 v[178:181], v159 offset:17408
	ds_read_b128 v[182:185], v159 offset:18432
	ds_read_b128 v[186:189], v159 offset:19456
	ds_read_b128 v[190:193], v159 offset:20480
	ds_read_b128 v[194:197], v159 offset:21504
	ds_read_b128 v[198:201], v159 offset:22528
	ds_read_b128 v[202:205], v159 offset:23552
	global_load_lds_dwordx4 v[154:155], off
	s_add_i32 m0, s18, 0x2000
	s_add_u32 s18, s22, 0x160000
	v_lshl_add_u64 v[206:207], s[22:23], 0, v[144:145]
	s_addc_u32 s19, s23, 0
	s_add_i32 s88, s89, s27
	global_load_lds_dwordx4 v[206:207], off
	v_lshl_add_u64 v[208:209], s[18:19], 0, v[176:177]
	s_mov_b32 m0, s88
	v_lshl_add_u64 v[210:211], s[24:25], 0, v[144:145]
	global_load_lds_dwordx4 v[208:209], off
	v_lshl_add_u64 v[208:209], s[18:19], 0, v[144:145]
	s_add_i32 m0, s88, 0x2000
	s_nop 0
	global_load_lds_dwordx4 v[208:209], off
	v_lshl_add_u64 v[208:209], s[24:25], 0, v[176:177]
	s_mov_b32 m0, s28
	s_nop 0
	global_load_lds_dwordx4 v[208:209], off
	s_mov_b32 m0, s29
	s_nop 0
	global_load_lds_dwordx4 v[210:211], off
	s_waitcnt vmcnt(8)
	s_waitcnt lgkmcnt(0)
	s_setprio 1
	s_barrier
	v_mfma_f32_16x16x32_bf16 v[60:63], v[128:131], v[172:175], v[60:63]
	v_mfma_f32_16x16x32_bf16 v[56:59], v[136:139], v[172:175], v[56:59]
	v_mfma_f32_16x16x32_bf16 v[52:55], v[128:131], v[182:185], v[52:55]
	v_mfma_f32_16x16x32_bf16 v[48:51], v[136:139], v[182:185], v[48:51]
	v_mfma_f32_16x16x32_bf16 v[44:47], v[128:131], v[190:193], v[44:47]
	v_mfma_f32_16x16x32_bf16 v[32:35], v[136:139], v[190:193], v[32:35]
	v_mfma_f32_16x16x32_bf16 v[16:19], v[128:131], v[198:201], v[16:19]
	v_mfma_f32_16x16x32_bf16 v[8:11], v[136:139], v[198:201], v[8:11]
	v_mfma_f32_16x16x32_bf16 v[60:63], v[132:135], v[178:181], v[60:63]
	v_mfma_f32_16x16x32_bf16 v[56:59], v[140:143], v[178:181], v[56:59]
	v_mfma_f32_16x16x32_bf16 v[52:55], v[132:135], v[186:189], v[52:55]
	v_mfma_f32_16x16x32_bf16 v[48:51], v[140:143], v[186:189], v[48:51]
	v_mfma_f32_16x16x32_bf16 v[44:47], v[132:135], v[194:197], v[44:47]
	v_mfma_f32_16x16x32_bf16 v[32:35], v[140:143], v[194:197], v[32:35]
	v_mfma_f32_16x16x32_bf16 v[16:19], v[132:135], v[202:205], v[16:19]
	v_mfma_f32_16x16x32_bf16 v[8:11], v[140:143], v[202:205], v[8:11]
	s_setprio 0
	s_setprio 1
	v_mfma_f32_16x16x32_bf16 v[40:43], v[150:153], v[172:175], v[40:43]
	v_mfma_f32_16x16x32_bf16 v[36:39], v[164:167], v[172:175], v[36:39]
	v_mfma_f32_16x16x32_bf16 v[28:31], v[150:153], v[182:185], v[28:31]
	v_mfma_f32_16x16x32_bf16 v[24:27], v[164:167], v[182:185], v[24:27]
	v_mfma_f32_16x16x32_bf16 v[20:23], v[150:153], v[190:193], v[20:23]
	v_mfma_f32_16x16x32_bf16 v[12:15], v[164:167], v[190:193], v[12:15]
	v_mfma_f32_16x16x32_bf16 v[4:7], v[150:153], v[198:201], v[4:7]
	v_mfma_f32_16x16x32_bf16 v[0:3], v[164:167], v[198:201], v[0:3]
	v_mfma_f32_16x16x32_bf16 v[40:43], v[160:163], v[178:181], v[40:43]
	v_mfma_f32_16x16x32_bf16 v[36:39], v[168:171], v[178:181], v[36:39]
	v_mfma_f32_16x16x32_bf16 v[28:31], v[160:163], v[186:189], v[28:31]
	v_mfma_f32_16x16x32_bf16 v[24:27], v[168:171], v[186:189], v[24:27]
	v_mfma_f32_16x16x32_bf16 v[20:23], v[160:163], v[194:197], v[20:23]
	v_mfma_f32_16x16x32_bf16 v[12:15], v[168:171], v[194:197], v[12:15]
	v_mfma_f32_16x16x32_bf16 v[4:7], v[160:163], v[202:205], v[4:7]
	v_mfma_f32_16x16x32_bf16 v[0:3], v[168:171], v[202:205], v[0:3]
	s_barrier
	s_setprio 0
	s_add_i32 s88, 0, 0x18000
	s_add_i32 s89, 0, 0x1c000
	v_add_u32_e32 v140, s88, v158
	v_add_u32_e32 v168, s89, v158
	ds_read_b128 v[128:131], v140
	ds_read_b128 v[132:135], v140 offset:1024
	ds_read_b128 v[136:139], v140 offset:2048
	ds_read_b128 v[140:143], v140 offset:3072
	ds_read_b128 v[150:153], v168
	ds_read_b128 v[160:163], v168 offset:1024
	ds_read_b128 v[164:167], v168 offset:2048
	ds_read_b128 v[168:171], v168 offset:3072
	s_add_u32 s18, s24, 0x160000
	s_addc_u32 s19, s25, 0
	s_mov_b32 m0, s30
	v_lshl_add_u64 v[212:213], s[18:19], 0, v[176:177]
	ds_read_b128 v[172:175], v159 offset:32768
	ds_read_b128 v[178:181], v159 offset:33792
	ds_read_b128 v[182:185], v159 offset:34816
	ds_read_b128 v[186:189], v159 offset:35840
	ds_read_b128 v[190:193], v159 offset:36864
	ds_read_b128 v[194:197], v159 offset:37888
	ds_read_b128 v[198:201], v159 offset:38912
	ds_read_b128 v[202:205], v159 offset:39936
	global_load_lds_dwordx4 v[212:213], off
	v_lshl_add_u64 v[212:213], s[18:19], 0, v[144:145]
	s_mov_b32 m0, s31
	s_nop 0
	global_load_lds_dwordx4 v[212:213], off
	s_waitcnt vmcnt(8)
	s_waitcnt lgkmcnt(0)
	s_setprio 1
	s_barrier
	v_mfma_f32_16x16x32_bf16 v[124:127], v[128:131], v[172:175], v[124:127]
	v_mfma_f32_16x16x32_bf16 v[120:123], v[136:139], v[172:175], v[120:123]
	v_mfma_f32_16x16x32_bf16 v[116:119], v[128:131], v[182:185], v[116:119]
	v_mfma_f32_16x16x32_bf16 v[112:115], v[136:139], v[182:185], v[112:115]
	v_mfma_f32_16x16x32_bf16 v[108:111], v[128:131], v[190:193], v[108:111]
	v_mfma_f32_16x16x32_bf16 v[100:103], v[136:139], v[190:193], v[100:103]
	v_mfma_f32_16x16x32_bf16 v[92:95], v[128:131], v[198:201], v[92:95]
	v_mfma_f32_16x16x32_bf16 v[72:75], v[136:139], v[198:201], v[72:75]
	v_mfma_f32_16x16x32_bf16 v[124:127], v[132:135], v[178:181], v[124:127]
	v_mfma_f32_16x16x32_bf16 v[120:123], v[140:143], v[178:181], v[120:123]
	v_mfma_f32_16x16x32_bf16 v[116:119], v[132:135], v[186:189], v[116:119]
	v_mfma_f32_16x16x32_bf16 v[112:115], v[140:143], v[186:189], v[112:115]
	v_mfma_f32_16x16x32_bf16 v[108:111], v[132:135], v[194:197], v[108:111]
	v_mfma_f32_16x16x32_bf16 v[100:103], v[140:143], v[194:197], v[100:103]
	v_mfma_f32_16x16x32_bf16 v[92:95], v[132:135], v[202:205], v[92:95]
	v_mfma_f32_16x16x32_bf16 v[72:75], v[140:143], v[202:205], v[72:75]
	s_setprio 0
	s_setprio 1
	v_mfma_f32_16x16x32_bf16 v[104:107], v[150:153], v[172:175], v[104:107]
	v_mfma_f32_16x16x32_bf16 v[96:99], v[164:167], v[172:175], v[96:99]
	v_mfma_f32_16x16x32_bf16 v[88:91], v[150:153], v[182:185], v[88:91]
	v_mfma_f32_16x16x32_bf16 v[84:87], v[164:167], v[182:185], v[84:87]
	v_mfma_f32_16x16x32_bf16 v[80:83], v[150:153], v[190:193], v[80:83]
	v_mfma_f32_16x16x32_bf16 v[76:79], v[164:167], v[190:193], v[76:79]
	v_mfma_f32_16x16x32_bf16 v[68:71], v[150:153], v[198:201], v[68:71]
	v_mfma_f32_16x16x32_bf16 v[64:67], v[164:167], v[198:201], v[64:67]
	v_mfma_f32_16x16x32_bf16 v[104:107], v[160:163], v[178:181], v[104:107]
	v_mfma_f32_16x16x32_bf16 v[96:99], v[168:171], v[178:181], v[96:99]
	v_mfma_f32_16x16x32_bf16 v[88:91], v[160:163], v[186:189], v[88:91]
	v_mfma_f32_16x16x32_bf16 v[84:87], v[168:171], v[186:189], v[84:87]
	v_mfma_f32_16x16x32_bf16 v[80:83], v[160:163], v[194:197], v[80:83]
	v_mfma_f32_16x16x32_bf16 v[76:79], v[168:171], v[194:197], v[76:79]
	v_mfma_f32_16x16x32_bf16 v[68:71], v[160:163], v[202:205], v[68:71]
	v_mfma_f32_16x16x32_bf16 v[64:67], v[168:171], v[202:205], v[64:67]
	s_barrier
	s_setprio 0
	s_add_i32 s18, s88, s27
	v_lshl_add_u64 v[154:155], v[154:155], 0, s[40:41]
	s_mov_b32 m0, s18
	ds_read_b128 v[172:175], v159 offset:49152
	ds_read_b128 v[178:181], v159 offset:50176
	ds_read_b128 v[182:185], v159 offset:51200
	ds_read_b128 v[186:189], v159 offset:52224
	ds_read_b128 v[190:193], v159 offset:53248
	ds_read_b128 v[194:197], v159 offset:54272
	ds_read_b128 v[198:201], v159 offset:55296
	ds_read_b128 v[202:205], v159 offset:56320
	global_load_lds_dwordx4 v[154:155], off
	s_add_i32 m0, s18, 0x2000
	s_add_u32 s18, s22, 0x160080
	v_lshl_add_u64 v[154:155], v[206:207], 0, s[40:41]
	s_addc_u32 s19, s23, 0
	s_add_i32 s22, s89, s27
	global_load_lds_dwordx4 v[154:155], off
	v_lshl_add_u64 v[154:155], s[18:19], 0, v[176:177]
	s_mov_b32 m0, s22
	s_nop 0
	global_load_lds_dwordx4 v[154:155], off
	v_lshl_add_u64 v[154:155], s[18:19], 0, v[144:145]
	s_add_i32 m0, s22, 0x2000
	s_nop 0
	global_load_lds_dwordx4 v[154:155], off
	v_lshl_add_u64 v[154:155], v[208:209], 0, s[40:41]
	s_mov_b32 m0, s37
	s_nop 0
	global_load_lds_dwordx4 v[154:155], off
	v_lshl_add_u64 v[154:155], v[210:211], 0, s[40:41]
	s_mov_b32 m0, s46
	s_nop 0
	global_load_lds_dwordx4 v[154:155], off
	s_waitcnt vmcnt(8)
	s_waitcnt lgkmcnt(0)
	s_setprio 1
	s_barrier
	v_mfma_f32_16x16x32_bf16 v[60:63], v[128:131], v[172:175], v[60:63]
	v_mfma_f32_16x16x32_bf16 v[56:59], v[136:139], v[172:175], v[56:59]
	v_mfma_f32_16x16x32_bf16 v[52:55], v[128:131], v[182:185], v[52:55]
	v_mfma_f32_16x16x32_bf16 v[48:51], v[136:139], v[182:185], v[48:51]
	v_mfma_f32_16x16x32_bf16 v[44:47], v[128:131], v[190:193], v[44:47]
	v_mfma_f32_16x16x32_bf16 v[32:35], v[136:139], v[190:193], v[32:35]
	v_mfma_f32_16x16x32_bf16 v[16:19], v[128:131], v[198:201], v[16:19]
	v_mfma_f32_16x16x32_bf16 v[8:11], v[136:139], v[198:201], v[8:11]
	v_mfma_f32_16x16x32_bf16 v[60:63], v[132:135], v[178:181], v[60:63]
	v_mfma_f32_16x16x32_bf16 v[56:59], v[140:143], v[178:181], v[56:59]
	v_mfma_f32_16x16x32_bf16 v[52:55], v[132:135], v[186:189], v[52:55]
	v_mfma_f32_16x16x32_bf16 v[48:51], v[140:143], v[186:189], v[48:51]
	v_mfma_f32_16x16x32_bf16 v[44:47], v[132:135], v[194:197], v[44:47]
	v_mfma_f32_16x16x32_bf16 v[32:35], v[140:143], v[194:197], v[32:35]
	v_mfma_f32_16x16x32_bf16 v[16:19], v[132:135], v[202:205], v[16:19]
	v_mfma_f32_16x16x32_bf16 v[8:11], v[140:143], v[202:205], v[8:11]
	s_setprio 0
	s_setprio 1
	v_mfma_f32_16x16x32_bf16 v[40:43], v[150:153], v[172:175], v[40:43]
	v_mfma_f32_16x16x32_bf16 v[36:39], v[164:167], v[172:175], v[36:39]
	v_mfma_f32_16x16x32_bf16 v[28:31], v[150:153], v[182:185], v[28:31]
	v_mfma_f32_16x16x32_bf16 v[24:27], v[164:167], v[182:185], v[24:27]
	v_mfma_f32_16x16x32_bf16 v[20:23], v[150:153], v[190:193], v[20:23]
	v_mfma_f32_16x16x32_bf16 v[12:15], v[164:167], v[190:193], v[12:15]
	v_mfma_f32_16x16x32_bf16 v[4:7], v[150:153], v[198:201], v[4:7]
	v_mfma_f32_16x16x32_bf16 v[0:3], v[164:167], v[198:201], v[0:3]
	v_mfma_f32_16x16x32_bf16 v[40:43], v[160:163], v[178:181], v[40:43]
	v_mfma_f32_16x16x32_bf16 v[36:39], v[168:171], v[178:181], v[36:39]
	v_mfma_f32_16x16x32_bf16 v[28:31], v[160:163], v[186:189], v[28:31]
	v_mfma_f32_16x16x32_bf16 v[24:27], v[168:171], v[186:189], v[24:27]
	v_mfma_f32_16x16x32_bf16 v[20:23], v[160:163], v[194:197], v[20:23]
	v_mfma_f32_16x16x32_bf16 v[12:15], v[168:171], v[194:197], v[12:15]
	v_mfma_f32_16x16x32_bf16 v[4:7], v[160:163], v[202:205], v[4:7]
	v_mfma_f32_16x16x32_bf16 v[0:3], v[168:171], v[202:205], v[0:3]
	s_barrier
	s_setprio 0
	s_add_u32 s49, s49, 0x100
	s_addc_u32 s96, s96, 0
	s_cmp_ge_u32 s97, s72
	s_mov_b64 s[18:19], s[20:21]
	s_mov_b32 s22, s97
	s_cbranch_scc0 .LBB0_1801
	s_and_b64 vcc, exec, s[10:11]
	s_cbranch_vccz .LBB0_1804
	s_barrier
